# attention step loop: complementary wave roles (waves 0-3 softmax-then-MFMA, waves 4-7 MFMA-then-softmax), loop bookkeeping in MFMA shadow
# speedup vs baseline: 1.0350x; 1.0007x over previous
; #define LAS __attribute__((address_space(3)))
; #define RING_ISSUE(SI) do { int kbi = kb0 + (SI) * 32; if (kbi > kb_last) kbi = kb_last; const int slot = (SI) % 3; \
;           const h16* srcp = wave < 4 ? kbase + (size_t)kbi * LDH + k_src_off : vT + (size_t)(kbi >> 5) * 2048 + v_src_off; \
;           __builtin_amdgcn_global_load_lds((const unsigned*)srcp, (LAS unsigned*)(ring + slot * 8192 + stage_dst), 16, 0, 0); } while (0)
; DI void attn_phase(const Params& p, const int layer, const int wid_s) {
;     ...
;         for (int si = 0; si < nsteps; ++si) {
;           asm volatile("s_waitcnt vmcnt(1) lgkmcnt(0)" ::: "memory");
;           __builtin_amdgcn_s_barrier();
;           asm volatile("" ::: "memory");
;           RING_ISSUE(si + 2);
;           const int kb = kb0 + si * 32;
;           if (kb > kmax_w || kb < lo_w) continue;
;           if (br == 1 && kb + 31 + 128 <= t0 && __ballot((selmask >> (kb >> 6)) & 1u) == 0ull) continue;
;           LAS unsigned char* slotp = ring + (si % 3) * 8192;
;           KF kv;
; #pragma unroll
;           for (int kt = 0; kt < 2; ++kt)
; #pragma unroll
;             for (int ks = 0; ks < 2; ++ks) kv.k[kt][ks] = *(const LAS half8*)(slotp + kread[kt][ks]);
; #pragma unroll
;           for (int dt = 0; dt < 4; ++dt) kv.v[dt] = *(const LAS half8*)(slotp + vread[dt]);
;           if (br == 1) {
;             const bool bit = (selmask >> (kb >> 6)) & 1u;
;             if (kb + 31 + 128 <= t0) attn_step<true, false>(kv, kb, t, lane, bit, tabh, q, O, nRs, l);
;             else attn_step<true, true>(kv, kb, t, lane, bit, tabh, q, O, nRs, l);
.Lat_precls:
	s_add_i32 s10, s45, 0x9f
	s_cmp_gt_i32 s10, s51
	s_cselect_b32 s11, 2, 0
	s_add_i32 s10, s45, 0x1f1
	s_cmp_le_i32 s10, s51
	s_cselect_b32 s10, 2, 0
	s_and_b32 s10, s10, s4
	s_or_b32 s11, s11, s10
	s_lshr_b32 s10, s45, 6
	v_bfe_u32 v0, v244, s10, 1
	v_cmp_ne_u32_e32 vcc, 0, v0
	s_cmp_lg_u64 vcc, 0
	s_cselect_b32 s10, 1, 0
	s_lshr_b32 s9, s11, 1
	s_or_b32 s10, s10, s9
	s_cmp_le_i32 s45, s15
	s_cselect_b32 s10, s10, 0
	s_cmp_ge_i32 s45, s40
	s_cselect_b32 s10, s10, 0
	s_or_b32 s12, s11, s10
	s_branch .LBB0_349
.LBB0_349:
	s_and_b64 vcc, exec, s[30:31]
	s_cbranch_vccnz .Lat_ytop
.Lat_xtop:
	s_waitcnt vmcnt(3)
	s_barrier
	s_bitcmp1_b32 s12, 0
	s_cbranch_scc0 .Lat_xskip
	v_add_u32_e32 v0, s39, v185
	v_add_u32_e32 v64, s39, v184
	v_add_u32_e32 v65, s39, v183
	ds_read_b128 v[96:99], v0
	ds_read_b128 v[92:95], v64
	ds_read_b128 v[88:91], v0 offset:2048
	ds_read_b128 v[84:87], v64 offset:2048
	s_lshr_b32 s10, s45, 6
	s_cmp_eq_u32 s10, s13
	s_cbranch_scc1 .Lat_cok_x
	s_mov_b32 s13, s10
	v_bfe_u32 v66, v244, s10, 1
	v_cmp_ne_u32_e32 vcc, 0, v66
	s_nop 1
	v_cndmask_b32_e32 v128, v4, v242, vcc
	v_cndmask_b32_e32 v132, v4, v243, vcc
	v_cndmask_b32_e32 v129, v4, v242, vcc
	v_cndmask_b32_e32 v133, v4, v243, vcc
	v_cndmask_b32_e32 v130, v4, v242, vcc
	v_cndmask_b32_e32 v134, v4, v243, vcc
	v_cndmask_b32_e32 v131, v4, v242, vcc
	v_cndmask_b32_e32 v135, v4, v243, vcc

; #define MFMA16(a, b, c) __builtin_amdgcn_mfma_f32_16x16x32_f16((a), (b), (c), 0, 0, 0)
; #define RING_ISSUE(SI) do { int kbi = kb0 + (SI) * 32; if (kbi > kb_last) kbi = kb_last; const int slot = (SI) % 3; \
;           const h16* srcp = wave < 4 ? kbase + (size_t)kbi * LDH + k_src_off : vT + (size_t)(kbi >> 5) * 2048 + v_src_off; \
;           __builtin_amdgcn_global_load_lds((const unsigned*)srcp, (LAS unsigned*)(ring + slot * 8192 + stage_dst), 16, 0, 0); } while (0)
; template <bool SEL, bool GEN>
; DI void attn_step(const KF& kv, const int kb, const int t, const int lane, const bool selbit,
;                   const LAS float* tabh, const half8 (&q)[2][2], f32x4 (&O)[2][4], const float (&nR)[2], float (&l)[2]) {
;     ...
;   for (int hp = 0; hp < 2; ++hp) {
;     float nm = nR[hp];
;     if (SEL) nm = selbit ? nm : MASKV;
;     const f32x4 c0 = {nm, nm, nm, nm};
; #pragma unroll
;     for (int kt = 0; kt < 2; ++kt) {
;       s[hp][kt] = MFMA16(kv.k[kt][0], q[hp][0], c0);
;       s[hp][kt] = MFMA16(kv.k[kt][1], q[hp][1], s[hp][kt]);
;     }
;   }
;   if (GEN) {
;     const int d0 = t - kb - fq * 4;
; #pragma unroll
;     for (int kt = 0; kt < 2; ++kt)
; #pragma unroll
;       for (int j = 0; j < 4; ++j) {
;         const int dist = d0 - (kt * 16 + j);
;         const bool bad = SEL ? (dist < 0) : ((unsigned)dist >= 512u);
;         const int ix = bad ? 130 : (dist > 128 ? 128 : dist);
; #pragma unroll
;         for (int hp = 0; hp < 2; ++hp) s[hp][kt][j] += tabh[hp * 132 + ix];
;       }
;   }
;   half8 pf[2];
; #pragma unroll
;   for (int hp = 0; hp < 2; ++hp) {
;     f32x4 p0, p1;
; #pragma unroll
;     for (int j = 0; j < 4; ++j) { p0[j] = __builtin_amdgcn_exp2f(s[hp][0][j]); p1[j] = __builtin_amdgcn_exp2f(s[hp][1][j]); }
;     l[hp] += ((p0[0] + p0[1]) + (p0[2] + p0[3])) + ((p1[0] + p1[1]) + (p1[2] + p1[3]));
;     pf[hp] = pack8(p0, p1);
;   }
; #pragma unroll
;   for (int dt = 0; dt < 4; ++dt)
; #pragma unroll
;     for (int hp = 0; hp < 2; ++hp) O[hp][dt] = MFMA16(kv.v[dt], pf[hp], O[hp][dt]);
; DI void attn_phase(const Params& p, const int layer, const int wid_s) {
;     ...
;           RING_ISSUE(si + 2);
;           const int kb = kb0 + si * 32;
;           if (kb > kmax_w || kb < lo_w) continue;
;           if (br == 1 && kb + 31 + 128 <= t0 && __ballot((selmask >> (kb >> 6)) & 1u) == 0ull) continue;
.Lat_nogen_xa:
	v_exp_f32_e32 v198, v100
	v_exp_f32_e32 v199, v101
	v_exp_f32_e32 v200, v102
	v_exp_f32_e32 v201, v103
	v_exp_f32_e32 v202, v104
	v_exp_f32_e32 v203, v105
	v_exp_f32_e32 v204, v106
	v_exp_f32_e32 v205, v107
	v_exp_f32_e32 v206, v108
	v_exp_f32_e32 v207, v109
	v_exp_f32_e32 v208, v110
	v_exp_f32_e32 v209, v111
	v_exp_f32_e32 v210, v112
	v_exp_f32_e32 v211, v113
	v_exp_f32_e32 v212, v114
	v_exp_f32_e32 v213, v115
	v_cvt_pkrtz_f16_f32 v120, v198, v199
	v_cvt_pkrtz_f16_f32 v121, v200, v201
	v_cvt_pkrtz_f16_f32 v122, v202, v203
	v_cvt_pkrtz_f16_f32 v123, v204, v205
	v_cvt_pkrtz_f16_f32 v124, v206, v207
	v_cvt_pkrtz_f16_f32 v125, v208, v209
	v_cvt_pkrtz_f16_f32 v126, v210, v211
	v_cvt_pkrtz_f16_f32 v127, v212, v213
	s_waitcnt lgkmcnt(0)
	v_mfma_f32_16x16x32_f16 v[60:63], v[80:83], v[120:123], v[60:63]
	v_add_f32_e32 v214, v214, v198
	v_add_f32_e32 v215, v215, v199
	v_add_f32_e32 v216, v216, v200
	v_mfma_f32_16x16x32_f16 v[56:59], v[76:79], v[120:123], v[56:59]
	v_add_f32_e32 v217, v217, v201
	v_add_f32_e32 v214, v214, v202
	v_add_f32_e32 v215, v215, v203
	v_mfma_f32_16x16x32_f16 v[52:55], v[72:75], v[120:123], v[52:55]
	v_add_f32_e32 v216, v216, v204
	v_add_f32_e32 v217, v217, v205
	v_add_f32_e32 v218, v218, v206
	v_mfma_f32_16x16x32_f16 v[48:51], v[68:71], v[120:123], v[48:51]
	v_add_f32_e32 v219, v219, v207
	v_add_f32_e32 v220, v220, v208
	v_add_f32_e32 v221, v221, v209
	v_mfma_f32_16x16x32_f16 v[44:47], v[80:83], v[124:127], v[44:47]
	v_add_f32_e32 v218, v218, v210
	v_add_f32_e32 v219, v219, v211
	v_add_f32_e32 v220, v220, v212
	v_mfma_f32_16x16x32_f16 v[40:43], v[76:79], v[124:127], v[40:43]
	v_add_f32_e32 v221, v221, v213
	s_add_i32 s8, s45, 128
	s_min_i32 s8, s8, s14
	v_mfma_f32_16x16x32_f16 v[36:39], v[72:75], v[124:127], v[36:39]
	s_mul_i32 s8, s8, s42
	s_mov_b32 s9, 0
	v_lshl_add_u64 v[238:239], v[240:241], 0, s[8:9]
	v_mfma_f32_16x16x32_f16 v[32:35], v[68:71], v[124:127], v[32:35]
	s_add_i32 m0, s43, s22
	s_nop 0
	global_load_lds_dwordx4 v[238:239], off
	v_subrev_u32_e32 v246, s45, v195
	s_and_b32 s44, s12, 2
	s_or_b32 s44, s44, 1
	v_mfma_f32_16x16x32_f16 v[100:103], v[96:99], v[8:11], v[128:131]
	s_add_i32 s43, s43, 0x2000
	s_cmp_eq_u32 s43, 0x1f880
	s_cselect_b32 s43, 0x20080, s43
	s_cmp_eq_u32 s43, 0x26080
	v_mfma_f32_16x16x32_f16 v[104:107], v[88:91], v[8:11], v[128:131]
	s_cselect_b32 s43, 0x19880, s43
	s_add_i32 s39, s39, 0x2000
	s_cmp_eq_u32 s39, 0x1f880
	s_cselect_b32 s39, 0x20080, s39
	v_mfma_f32_16x16x32_f16 v[108:111], v[96:99], v[16:19], v[132:135]
	s_cmp_eq_u32 s39, 0x26080
	s_cselect_b32 s39, 0x19880, s39
	s_add_i32 s45, s45, 32
	s_add_i32 s41, s41, -1
	v_mfma_f32_16x16x32_f16 v[112:115], v[88:91], v[16:19], v[132:135]
	s_add_i32 s10, s45, 0x9f
	s_cmp_gt_i32 s10, s51
	s_cselect_b32 s11, 2, 0
	s_add_i32 s10, s45, 0x1f1
	v_mfma_f32_16x16x32_f16 v[100:103], v[92:95], v[12:15], v[100:103]
	s_cmp_le_i32 s10, s51
	s_cselect_b32 s10, 2, 0
	s_and_b32 s10, s10, s4
	s_or_b32 s11, s11, s10
	v_mfma_f32_16x16x32_f16 v[104:107], v[84:87], v[12:15], v[104:107]
	s_lshr_b32 s10, s45, 6
	v_bfe_u32 v0, v244, s10, 1
	v_cmp_ne_u32_e32 vcc, 0, v0
	s_cmp_lg_u64 vcc, 0
	v_mfma_f32_16x16x32_f16 v[108:111], v[92:95], v[20:23], v[108:111]
	s_cselect_b32 s10, 1, 0
	s_lshr_b32 s9, s11, 1
	s_or_b32 s10, s10, s9
	s_cmp_le_i32 s45, s15
	v_mfma_f32_16x16x32_f16 v[112:115], v[84:87], v[20:23], v[112:115]
	s_cselect_b32 s10, s10, 0
	s_cmp_ge_i32 s45, s40
	s_cselect_b32 s10, s10, 0
	s_or_b32 s12, s11, s10
	ds_read_b128 v[80:83], v65 offset:4096
	ds_read_b128 v[76:79], v65 offset:5120
	ds_read_b128 v[72:75], v65 offset:6144
	ds_read_b128 v[68:71], v65 offset:7168
	s_cmp_lg_u32 s41, 0
	s_cbranch_scc1 .Lat_xtop
	s_branch .Lat_xexit
.Lat_xb:
	s_waitcnt lgkmcnt(0)
	v_subrev_u32_e32 v246, s45, v195
	s_and_b32 s44, s12, 2
	s_or_b32 s44, s44, 1
	v_mfma_f32_16x16x32_f16 v[100:103], v[96:99], v[8:11], v[128:131]
	s_add_i32 s8, s45, 128
	s_min_i32 s8, s8, s14
	s_mul_i32 s8, s8, s42
	s_mov_b32 s9, 0
	v_lshl_add_u64 v[238:239], v[240:241], 0, s[8:9]
	v_mfma_f32_16x16x32_f16 v[104:107], v[88:91], v[8:11], v[128:131]
	s_add_i32 m0, s43, s22
	s_nop 0
	global_load_lds_dwordx4 v[238:239], off
	s_add_i32 s43, s43, 0x2000
	s_cmp_eq_u32 s43, 0x1f880
	v_mfma_f32_16x16x32_f16 v[108:111], v[96:99], v[16:19], v[132:135]
	s_cselect_b32 s43, 0x20080, s43
	s_cmp_eq_u32 s43, 0x26080
	s_cselect_b32 s43, 0x19880, s43
	s_add_i32 s39, s39, 0x2000
	s_cmp_eq_u32 s39, 0x1f880
	v_mfma_f32_16x16x32_f16 v[112:115], v[88:91], v[16:19], v[132:135]
	s_cselect_b32 s39, 0x20080, s39
	s_cmp_eq_u32 s39, 0x26080
	s_cselect_b32 s39, 0x19880, s39
	s_add_i32 s45, s45, 32
	s_add_i32 s41, s41, -1
	v_mfma_f32_16x16x32_f16 v[100:103], v[92:95], v[12:15], v[100:103]
	s_add_i32 s10, s45, 0x9f
	s_cmp_gt_i32 s10, s51
	s_cselect_b32 s11, 2, 0
	s_add_i32 s10, s45, 0x1f1
	s_cmp_le_i32 s10, s51
	v_mfma_f32_16x16x32_f16 v[104:107], v[84:87], v[12:15], v[104:107]
	s_cselect_b32 s10, 2, 0
	s_and_b32 s10, s10, s4
	s_or_b32 s11, s11, s10
	s_lshr_b32 s10, s45, 6
	v_bfe_u32 v0, v244, s10, 1
	v_mfma_f32_16x16x32_f16 v[108:111], v[92:95], v[20:23], v[108:111]
	v_cmp_ne_u32_e32 vcc, 0, v0
	s_cmp_lg_u64 vcc, 0
	s_cselect_b32 s10, 1, 0
	s_lshr_b32 s9, s11, 1
	s_or_b32 s10, s10, s9
	v_mfma_f32_16x16x32_f16 v[112:115], v[84:87], v[20:23], v[112:115]
	s_cmp_le_i32 s45, s15
	s_cselect_b32 s10, s10, 0
	s_cmp_ge_i32 s45, s40
	s_cselect_b32 s10, s10, 0
	s_or_b32 s12, s11, s10
	ds_read_b128 v[80:83], v65 offset:4096
	ds_read_b128 v[76:79], v65 offset:5120
	ds_read_b128 v[72:75], v65 offset:6144
	ds_read_b128 v[68:71], v65 offset:7168
	s_cmp_lg_u32 s41, 0
	s_cbranch_scc1 .Lat_xtop
	s_branch .Lat_xexit

; #define MFMA16(a, b, c) __builtin_amdgcn_mfma_f32_16x16x32_f16((a), (b), (c), 0, 0, 0)
; #define RING_ISSUE(SI) do { int kbi = kb0 + (SI) * 32; if (kbi > kb_last) kbi = kb_last; const int slot = (SI) % 3; \
;           const h16* srcp = wave < 4 ? kbase + (size_t)kbi * LDH + k_src_off : vT + (size_t)(kbi >> 5) * 2048 + v_src_off; \
;           __builtin_amdgcn_global_load_lds((const unsigned*)srcp, (LAS unsigned*)(ring + slot * 8192 + stage_dst), 16, 0, 0); } while (0)
; template <bool SEL, bool GEN>
; DI void attn_step(const KF& kv, const int kb, const int t, const int lane, const bool selbit,
;                   const LAS float* tabh, const half8 (&q)[2][2], f32x4 (&O)[2][4], const float (&nR)[2], float (&l)[2]) {
;     ...
;   if (GEN) {
;     const int d0 = t - kb - fq * 4;
; #pragma unroll
;     for (int kt = 0; kt < 2; ++kt)
; #pragma unroll
;       for (int j = 0; j < 4; ++j) {
;         const int dist = d0 - (kt * 16 + j);
;         const bool bad = SEL ? (dist < 0) : ((unsigned)dist >= 512u);
;         const int ix = bad ? 130 : (dist > 128 ? 128 : dist);
; #pragma unroll
;         for (int hp = 0; hp < 2; ++hp) s[hp][kt][j] += tabh[hp * 132 + ix];
;       }
;   }
;   half8 pf[2];
; #pragma unroll
;   for (int hp = 0; hp < 2; ++hp) {
;     f32x4 p0, p1;
; #pragma unroll
;     for (int j = 0; j < 4; ++j) { p0[j] = __builtin_amdgcn_exp2f(s[hp][0][j]); p1[j] = __builtin_amdgcn_exp2f(s[hp][1][j]); }
;     l[hp] += ((p0[0] + p0[1]) + (p0[2] + p0[3])) + ((p1[0] + p1[1]) + (p1[2] + p1[3]));
;     pf[hp] = pack8(p0, p1);
;   }
; #pragma unroll
;   for (int dt = 0; dt < 4; ++dt)
; #pragma unroll
;     for (int hp = 0; hp < 2; ++hp) O[hp][dt] = MFMA16(kv.v[dt], pf[hp], O[hp][dt]);
; DI void attn_phase(const Params& p, const int layer, const int wid_s) {
;     ...
;           RING_ISSUE(si + 2);
;           const int kb = kb0 + si * 32;
;           if (kb > kmax_w || kb < lo_w) continue;
;           if (br == 1 && kb + 31 + 128 <= t0 && __ballot((selmask >> (kb >> 6)) & 1u) == 0ull) continue;
.Lat_nogen_xc:
	v_exp_f32_e32 v198, v100
	v_exp_f32_e32 v199, v101
	v_exp_f32_e32 v200, v102
	v_exp_f32_e32 v201, v103
	v_exp_f32_e32 v202, v104
	v_exp_f32_e32 v203, v105
	v_exp_f32_e32 v204, v106
	v_exp_f32_e32 v205, v107
	v_exp_f32_e32 v206, v108
	v_exp_f32_e32 v207, v109
	v_exp_f32_e32 v208, v110
	v_exp_f32_e32 v209, v111
	v_exp_f32_e32 v210, v112
	v_exp_f32_e32 v211, v113
	v_exp_f32_e32 v212, v114
	v_exp_f32_e32 v213, v115
	v_cvt_pkrtz_f16_f32 v120, v198, v199
	v_cvt_pkrtz_f16_f32 v121, v200, v201
	v_cvt_pkrtz_f16_f32 v122, v202, v203
	v_cvt_pkrtz_f16_f32 v123, v204, v205
	v_cvt_pkrtz_f16_f32 v124, v206, v207
	v_cvt_pkrtz_f16_f32 v125, v208, v209
	v_cvt_pkrtz_f16_f32 v126, v210, v211
	v_cvt_pkrtz_f16_f32 v127, v212, v213
	s_waitcnt lgkmcnt(0)
	v_mfma_f32_16x16x32_f16 v[60:63], v[80:83], v[120:123], v[60:63]
	v_add_f32_e32 v214, v214, v198
	v_add_f32_e32 v215, v215, v199
	v_add_f32_e32 v216, v216, v200
	v_add_f32_e32 v217, v217, v201
	v_add_f32_e32 v214, v214, v202
	v_add_f32_e32 v215, v215, v203
	v_add_f32_e32 v216, v216, v204
	v_mfma_f32_16x16x32_f16 v[56:59], v[76:79], v[120:123], v[56:59]
	v_add_f32_e32 v217, v217, v205
	v_add_f32_e32 v218, v218, v206
	v_add_f32_e32 v219, v219, v207
	v_add_f32_e32 v220, v220, v208
	v_add_f32_e32 v221, v221, v209
	v_add_f32_e32 v218, v218, v210
	v_add_f32_e32 v219, v219, v211
	v_mfma_f32_16x16x32_f16 v[52:55], v[72:75], v[120:123], v[52:55]
	v_add_f32_e32 v220, v220, v212
	v_add_f32_e32 v221, v221, v213
	s_add_i32 s8, s45, 128
	s_min_i32 s8, s8, s14
	s_mul_i32 s8, s8, s42
	s_mov_b32 s9, 0
	v_lshl_add_u64 v[238:239], v[240:241], 0, s[8:9]
	v_mfma_f32_16x16x32_f16 v[48:51], v[68:71], v[120:123], v[48:51]
	s_add_i32 m0, s43, s22
	s_nop 0
	global_load_lds_dwordx4 v[238:239], off
	s_add_i32 s43, s43, 0x2000
	s_cmp_eq_u32 s43, 0x1f880
	s_cselect_b32 s43, 0x20080, s43
	s_cmp_eq_u32 s43, 0x26080
	v_mfma_f32_16x16x32_f16 v[44:47], v[80:83], v[124:127], v[44:47]
	s_cselect_b32 s43, 0x19880, s43
	s_add_i32 s39, s39, 0x2000
	s_cmp_eq_u32 s39, 0x1f880
	s_cselect_b32 s39, 0x20080, s39
	s_cmp_eq_u32 s39, 0x26080
	s_cselect_b32 s39, 0x19880, s39
	s_add_i32 s45, s45, 32
	v_mfma_f32_16x16x32_f16 v[40:43], v[76:79], v[124:127], v[40:43]
	s_add_i32 s41, s41, -1
	s_add_i32 s10, s45, 0x9f
	s_cmp_gt_i32 s10, s51
	s_cselect_b32 s11, 2, 0
	s_add_i32 s10, s45, 0x1f1
	s_cmp_le_i32 s10, s51
	s_cselect_b32 s10, 2, 0
	v_mfma_f32_16x16x32_f16 v[36:39], v[72:75], v[124:127], v[36:39]
	s_and_b32 s10, s10, s4
	s_or_b32 s11, s11, s10
	s_lshr_b32 s10, s45, 6
	v_bfe_u32 v0, v244, s10, 1
	v_cmp_ne_u32_e32 vcc, 0, v0
	s_cmp_lg_u64 vcc, 0
	s_cselect_b32 s10, 1, 0
	v_mfma_f32_16x16x32_f16 v[32:35], v[68:71], v[124:127], v[32:35]
	s_lshr_b32 s9, s11, 1
	s_or_b32 s10, s10, s9
	s_cmp_le_i32 s45, s15
	s_cselect_b32 s10, s10, 0
	s_cmp_ge_i32 s45, s40
	s_cselect_b32 s10, s10, 0
	s_or_b32 s12, s11, s10
	s_mov_b32 s44, 0
	s_cmp_lg_u32 s41, 0
	s_cbranch_scc1 .Lat_xtop
	s_branch .Lat_xexit
.Lat_xd:
	s_add_i32 s8, s45, 128
	s_min_i32 s8, s8, s14
	s_mul_i32 s8, s8, s42
	s_mov_b32 s9, 0
	v_lshl_add_u64 v[238:239], v[240:241], 0, s[8:9]
	s_add_i32 m0, s43, s22
	s_nop 0
	global_load_lds_dwordx4 v[238:239], off
	s_add_i32 s43, s43, 0x2000
	s_cmp_eq_u32 s43, 0x1f880
	s_cselect_b32 s43, 0x20080, s43
	s_cmp_eq_u32 s43, 0x26080
	s_cselect_b32 s43, 0x19880, s43
	s_add_i32 s39, s39, 0x2000
	s_cmp_eq_u32 s39, 0x1f880
	s_cselect_b32 s39, 0x20080, s39
	s_cmp_eq_u32 s39, 0x26080
	s_cselect_b32 s39, 0x19880, s39
	s_add_i32 s45, s45, 32
	s_add_i32 s41, s41, -1
	s_add_i32 s10, s45, 0x9f
	s_cmp_gt_i32 s10, s51
	s_cselect_b32 s11, 2, 0
	s_add_i32 s10, s45, 0x1f1
	s_cmp_le_i32 s10, s51
	s_cselect_b32 s10, 2, 0
	s_and_b32 s10, s10, s4
	s_or_b32 s11, s11, s10
	s_lshr_b32 s10, s45, 6
	v_bfe_u32 v0, v244, s10, 1
	v_cmp_ne_u32_e32 vcc, 0, v0
	s_cmp_lg_u64 vcc, 0
	s_cselect_b32 s10, 1, 0
	s_lshr_b32 s9, s11, 1
	s_or_b32 s10, s10, s9
	s_cmp_le_i32 s45, s15
	s_cselect_b32 s10, s10, 0
	s_cmp_ge_i32 s45, s40
	s_cselect_b32 s10, s10, 0
	s_or_b32 s12, s11, s10
	s_cmp_lg_u32 s41, 0
	s_cbranch_scc1 .Lat_xtop

; #define MFMA16(a, b, c) __builtin_amdgcn_mfma_f32_16x16x32_f16((a), (b), (c), 0, 0, 0)
; template <bool SEL, bool GEN>
; DI void attn_step(const KF& kv, const int kb, const int t, const int lane, const bool selbit,
;                   const LAS float* tabh, const half8 (&q)[2][2], f32x4 (&O)[2][4], const float (&nR)[2], float (&l)[2]) {
;     ...
;   half8 pf[2];
; #pragma unroll
;   for (int hp = 0; hp < 2; ++hp) {
;     f32x4 p0, p1;
; #pragma unroll
;     for (int j = 0; j < 4; ++j) { p0[j] = __builtin_amdgcn_exp2f(s[hp][0][j]); p1[j] = __builtin_amdgcn_exp2f(s[hp][1][j]); }
;     l[hp] += ((p0[0] + p0[1]) + (p0[2] + p0[3])) + ((p1[0] + p1[1]) + (p1[2] + p1[3]));
;     pf[hp] = pack8(p0, p1);
;   }
; #pragma unroll
;   for (int dt = 0; dt < 4; ++dt)
; #pragma unroll
;     for (int hp = 0; hp < 2; ++hp) O[hp][dt] = MFMA16(kv.v[dt], pf[hp], O[hp][dt]);
.Lat_nogen_xx:
	v_exp_f32_e32 v198, v100
	v_exp_f32_e32 v199, v101
	v_exp_f32_e32 v200, v102
	v_exp_f32_e32 v201, v103
	v_exp_f32_e32 v202, v104
	v_exp_f32_e32 v203, v105
	v_exp_f32_e32 v204, v106
	v_exp_f32_e32 v205, v107
	v_exp_f32_e32 v206, v108
	v_exp_f32_e32 v207, v109
	v_exp_f32_e32 v208, v110
	v_exp_f32_e32 v209, v111
	v_exp_f32_e32 v210, v112
	v_exp_f32_e32 v211, v113
	v_exp_f32_e32 v212, v114
	v_exp_f32_e32 v213, v115
	v_cvt_pkrtz_f16_f32 v120, v198, v199
	v_cvt_pkrtz_f16_f32 v121, v200, v201
	v_cvt_pkrtz_f16_f32 v122, v202, v203
	v_cvt_pkrtz_f16_f32 v123, v204, v205
	v_cvt_pkrtz_f16_f32 v124, v206, v207
	v_cvt_pkrtz_f16_f32 v125, v208, v209
	v_cvt_pkrtz_f16_f32 v126, v210, v211
	v_cvt_pkrtz_f16_f32 v127, v212, v213
	s_waitcnt lgkmcnt(0)
	v_mfma_f32_16x16x32_f16 v[60:63], v[80:83], v[120:123], v[60:63]
	v_add_f32_e32 v214, v214, v198
	v_add_f32_e32 v215, v215, v199
	v_mfma_f32_16x16x32_f16 v[56:59], v[76:79], v[120:123], v[56:59]
	v_add_f32_e32 v216, v216, v200
	v_add_f32_e32 v217, v217, v201
	v_mfma_f32_16x16x32_f16 v[52:55], v[72:75], v[120:123], v[52:55]
	v_add_f32_e32 v214, v214, v202
	v_add_f32_e32 v215, v215, v203
	v_mfma_f32_16x16x32_f16 v[48:51], v[68:71], v[120:123], v[48:51]
	v_add_f32_e32 v216, v216, v204
	v_add_f32_e32 v217, v217, v205
	v_mfma_f32_16x16x32_f16 v[44:47], v[80:83], v[124:127], v[44:47]
	v_add_f32_e32 v218, v218, v206
	v_add_f32_e32 v219, v219, v207
	v_mfma_f32_16x16x32_f16 v[40:43], v[76:79], v[124:127], v[40:43]
	v_add_f32_e32 v220, v220, v208
	v_add_f32_e32 v221, v221, v209
	v_mfma_f32_16x16x32_f16 v[36:39], v[72:75], v[124:127], v[36:39]
	v_add_f32_e32 v218, v218, v210
	v_add_f32_e32 v219, v219, v211
	v_mfma_f32_16x16x32_f16 v[32:35], v[68:71], v[124:127], v[32:35]
	v_add_f32_e32 v220, v220, v212
	v_add_f32_e32 v221, v221, v213
	s_branch .Lat_done

; #define MFMA16(a, b, c) __builtin_amdgcn_mfma_f32_16x16x32_f16((a), (b), (c), 0, 0, 0)
; #define RING_ISSUE(SI) do { int kbi = kb0 + (SI) * 32; if (kbi > kb_last) kbi = kb_last; const int slot = (SI) % 3; \
;           const h16* srcp = wave < 4 ? kbase + (size_t)kbi * LDH + k_src_off : vT + (size_t)(kbi >> 5) * 2048 + v_src_off; \
;           __builtin_amdgcn_global_load_lds((const unsigned*)srcp, (LAS unsigned*)(ring + slot * 8192 + stage_dst), 16, 0, 0); } while (0)
; template <bool SEL, bool GEN>
; DI void attn_step(const KF& kv, const int kb, const int t, const int lane, const bool selbit,
;                   const LAS float* tabh, const half8 (&q)[2][2], f32x4 (&O)[2][4], const float (&nR)[2], float (&l)[2]) {
;     ...
;   for (int hp = 0; hp < 2; ++hp) {
;     float nm = nR[hp];
;     if (SEL) nm = selbit ? nm : MASKV;
;     const f32x4 c0 = {nm, nm, nm, nm};
; #pragma unroll
;     for (int kt = 0; kt < 2; ++kt) {
;       s[hp][kt] = MFMA16(kv.k[kt][0], q[hp][0], c0);
;       s[hp][kt] = MFMA16(kv.k[kt][1], q[hp][1], s[hp][kt]);
;     }
;   }
;   if (GEN) {
;     const int d0 = t - kb - fq * 4;
; #pragma unroll
;     for (int kt = 0; kt < 2; ++kt)
; #pragma unroll
;       for (int j = 0; j < 4; ++j) {
;         const int dist = d0 - (kt * 16 + j);
;         const bool bad = SEL ? (dist < 0) : ((unsigned)dist >= 512u);
;         const int ix = bad ? 130 : (dist > 128 ? 128 : dist);
; #pragma unroll
;         for (int hp = 0; hp < 2; ++hp) s[hp][kt][j] += tabh[hp * 132 + ix];
;       }
;   }
;   half8 pf[2];
; #pragma unroll
;   for (int hp = 0; hp < 2; ++hp) {
;     f32x4 p0, p1;
; #pragma unroll
;     for (int j = 0; j < 4; ++j) { p0[j] = __builtin_amdgcn_exp2f(s[hp][0][j]); p1[j] = __builtin_amdgcn_exp2f(s[hp][1][j]); }
;     l[hp] += ((p0[0] + p0[1]) + (p0[2] + p0[3])) + ((p1[0] + p1[1]) + (p1[2] + p1[3]));
;     pf[hp] = pack8(p0, p1);
;   }
; #pragma unroll
;   for (int dt = 0; dt < 4; ++dt)
; #pragma unroll
;     for (int hp = 0; hp < 2; ++hp) O[hp][dt] = MFMA16(kv.v[dt], pf[hp], O[hp][dt]);
; DI void attn_phase(const Params& p, const int layer, const int wid_s) {
;     ...
;           RING_ISSUE(si + 2);
;           const int kb = kb0 + si * 32;
;           if (kb > kmax_w || kb < lo_w) continue;
;           if (br == 1 && kb + 31 + 128 <= t0 && __ballot((selmask >> (kb >> 6)) & 1u) == 0ull) continue;
.Lat_cok_y:
	s_bitcmp1_b32 s44, 0
	s_cbranch_scc0 .Lat_yb
	s_waitcnt lgkmcnt(4)
	v_mfma_f32_16x16x32_f16 v[60:63], v[80:83], v[120:123], v[60:63]
	v_add_f32_e32 v214, v214, v198
	v_add_f32_e32 v215, v215, v199
	v_add_f32_e32 v216, v216, v200
	v_mfma_f32_16x16x32_f16 v[56:59], v[76:79], v[120:123], v[56:59]
	v_add_f32_e32 v217, v217, v201
	v_add_f32_e32 v214, v214, v202
	v_add_f32_e32 v215, v215, v203
	v_mfma_f32_16x16x32_f16 v[52:55], v[72:75], v[120:123], v[52:55]
	v_add_f32_e32 v216, v216, v204
	v_add_f32_e32 v217, v217, v205
	v_add_f32_e32 v218, v218, v206
	v_mfma_f32_16x16x32_f16 v[48:51], v[68:71], v[120:123], v[48:51]
	v_add_f32_e32 v219, v219, v207
	v_add_f32_e32 v220, v220, v208
	v_add_f32_e32 v221, v221, v209
	v_mfma_f32_16x16x32_f16 v[44:47], v[80:83], v[124:127], v[44:47]
	v_add_f32_e32 v218, v218, v210
	v_add_f32_e32 v219, v219, v211
	v_add_f32_e32 v220, v220, v212
	v_mfma_f32_16x16x32_f16 v[40:43], v[76:79], v[124:127], v[40:43]
	v_add_f32_e32 v221, v221, v213
	s_add_i32 s8, s45, 128
	s_min_i32 s8, s8, s14
	v_mfma_f32_16x16x32_f16 v[36:39], v[72:75], v[124:127], v[36:39]
	s_mul_i32 s8, s8, s42
	s_mov_b32 s9, 0
	v_lshl_add_u64 v[238:239], v[240:241], 0, s[8:9]
	v_mfma_f32_16x16x32_f16 v[32:35], v[68:71], v[124:127], v[32:35]
	s_add_i32 m0, s43, s22
	s_nop 0
	global_load_lds_dwordx4 v[238:239], off
	s_waitcnt lgkmcnt(0)
	v_subrev_u32_e32 v246, s45, v195
	s_and_b32 s44, s12, 2
	s_or_b32 s44, s44, 1
	v_mfma_f32_16x16x32_f16 v[100:103], v[96:99], v[8:11], v[128:131]
	s_add_i32 s43, s43, 0x2000
	s_cmp_eq_u32 s43, 0x1f880
	s_cselect_b32 s43, 0x20080, s43
	s_cmp_eq_u32 s43, 0x26080
	v_mfma_f32_16x16x32_f16 v[104:107], v[88:91], v[8:11], v[128:131]
	s_cselect_b32 s43, 0x19880, s43
	s_add_i32 s39, s39, 0x2000
	s_cmp_eq_u32 s39, 0x1f880
	s_cselect_b32 s39, 0x20080, s39
	v_mfma_f32_16x16x32_f16 v[108:111], v[96:99], v[16:19], v[132:135]
	s_cmp_eq_u32 s39, 0x26080
	s_cselect_b32 s39, 0x19880, s39
	s_add_i32 s45, s45, 32
	s_add_i32 s41, s41, -1
	v_mfma_f32_16x16x32_f16 v[112:115], v[88:91], v[16:19], v[132:135]
	s_add_i32 s10, s45, 0x9f
	s_cmp_gt_i32 s10, s51
	s_cselect_b32 s11, 2, 0
	s_add_i32 s10, s45, 0x1f1
	v_mfma_f32_16x16x32_f16 v[100:103], v[92:95], v[12:15], v[100:103]
	s_cmp_le_i32 s10, s51
	s_cselect_b32 s10, 2, 0
	s_and_b32 s10, s10, s4
	s_or_b32 s11, s11, s10
	v_mfma_f32_16x16x32_f16 v[104:107], v[84:87], v[12:15], v[104:107]
	s_lshr_b32 s10, s45, 6
	v_bfe_u32 v0, v244, s10, 1
	v_cmp_ne_u32_e32 vcc, 0, v0
	s_cmp_lg_u64 vcc, 0
	v_mfma_f32_16x16x32_f16 v[108:111], v[92:95], v[20:23], v[108:111]
	s_cselect_b32 s10, 1, 0
	s_lshr_b32 s9, s11, 1
	s_or_b32 s10, s10, s9
	s_cmp_le_i32 s45, s15
	v_mfma_f32_16x16x32_f16 v[112:115], v[84:87], v[20:23], v[112:115]
	s_cselect_b32 s10, s10, 0
	s_cmp_ge_i32 s45, s40
	s_cselect_b32 s10, s10, 0
	s_or_b32 s12, s11, s10
	ds_read_b128 v[80:83], v65 offset:4096
	ds_read_b128 v[76:79], v65 offset:5120
	ds_read_b128 v[72:75], v65 offset:6144
	ds_read_b128 v[68:71], v65 offset:7168
	s_bitcmp1_b32 s44, 1
	s_cbranch_scc0 .Lat_nogen_ya
	v_add_u32_e32 v116, 19, v246
	v_add_u32_e32 v117, 18, v246
	v_cmp_gt_u32_e64 s[8:9], v247, v116
	v_cmp_gt_u32_e64 vcc, v247, v117
	v_min_u32_e32 v116, 0x80, v116
	v_min_u32_e32 v117, 0x80, v117
	v_cndmask_b32_e64 v116, v161, v116, s[8:9]
	v_cndmask_b32_e64 v117, v161, v117, vcc
	v_lshl_add_u32 v116, v116, 2, s38
	v_lshl_add_u32 v117, v117, 2, s38
	ds_read2_b32 v[222:223], v116 offset1:132
	ds_read2_b32 v[224:225], v117 offset1:132
	v_add_u32_e32 v116, 17, v246
	v_add_u32_e32 v117, 16, v246
	v_cmp_gt_u32_e64 s[8:9], v247, v116
	v_cmp_gt_u32_e64 vcc, v247, v117
	v_min_u32_e32 v116, 0x80, v116
	v_min_u32_e32 v117, 0x80, v117
	v_cndmask_b32_e64 v116, v161, v116, s[8:9]
	v_cndmask_b32_e64 v117, v161, v117, vcc
	v_lshl_add_u32 v116, v116, 2, s38
	v_lshl_add_u32 v117, v117, 2, s38
	ds_read2_b32 v[226:227], v116 offset1:132
	ds_read2_b32 v[228:229], v117 offset1:132
	v_add_u32_e32 v116, 3, v246
	v_add_u32_e32 v117, 2, v246
	v_cmp_gt_u32_e64 s[8:9], v247, v116
	v_cmp_gt_u32_e64 vcc, v247, v117
	v_min_u32_e32 v116, 0x80, v116
	v_min_u32_e32 v117, 0x80, v117
	v_cndmask_b32_e64 v116, v161, v116, s[8:9]
	v_cndmask_b32_e64 v117, v161, v117, vcc
	v_lshl_add_u32 v116, v116, 2, s38
	v_lshl_add_u32 v117, v117, 2, s38
	ds_read2_b32 v[230:231], v116 offset1:132
	ds_read2_b32 v[232:233], v117 offset1:132
	v_add_u32_e32 v116, 1, v246
	v_add_u32_e32 v117, 0, v246
	v_cmp_gt_u32_e64 s[8:9], v247, v116
	v_cmp_gt_u32_e64 vcc, v247, v117
	v_min_u32_e32 v116, 0x80, v116
	v_min_u32_e32 v117, 0x80, v117
	v_cndmask_b32_e64 v116, v161, v116, s[8:9]
	v_cndmask_b32_e64 v117, v161, v117, vcc
	v_lshl_add_u32 v116, v116, 2, s38
	v_lshl_add_u32 v117, v117, 2, s38
	ds_read2_b32 v[234:235], v116 offset1:132
	ds_read2_b32 v[236:237], v117 offset1:132
	s_waitcnt lgkmcnt(0)
	v_add_f32_e32 v100, v100, v222
	v_add_f32_e32 v108, v108, v223
	v_add_f32_e32 v101, v101, v224
	v_add_f32_e32 v109, v109, v225
	v_add_f32_e32 v102, v102, v226
	v_add_f32_e32 v110, v110, v227
	v_add_f32_e32 v103, v103, v228
	v_add_f32_e32 v111, v111, v229
	v_add_f32_e32 v104, v104, v230
	v_add_f32_e32 v112, v112, v231
	v_add_f32_e32 v105, v105, v232
	v_add_f32_e32 v113, v113, v233
	v_add_f32_e32 v106, v106, v234
	v_add_f32_e32 v114, v114, v235
	v_add_f32_e32 v107, v107, v236
	v_add_f32_e32 v115, v115, v237
; #define MFMA16(a, b, c) __builtin_amdgcn_mfma_f32_16x16x32_f16((a), (b), (c), 0, 0, 0)
; template <bool SEL, bool GEN>
; DI void attn_step(const KF& kv, const int kb, const int t, const int lane, const bool selbit,
;                   const LAS float* tabh, const half8 (&q)[2][2], f32x4 (&O)[2][4], const float (&nR)[2], float (&l)[2]) {
;     ...
;   for (int hp = 0; hp < 2; ++hp) {
;     float nm = nR[hp];
;     if (SEL) nm = selbit ? nm : MASKV;
;     const f32x4 c0 = {nm, nm, nm, nm};
; #pragma unroll
;     for (int kt = 0; kt < 2; ++kt) {
;       s[hp][kt] = MFMA16(kv.k[kt][0], q[hp][0], c0);
;       s[hp][kt] = MFMA16(kv.k[kt][1], q[hp][1], s[hp][kt]);
;     }
;   }
;   if (GEN) {
;     const int d0 = t - kb - fq * 4;
; #pragma unroll
;     for (int kt = 0; kt < 2; ++kt)
; #pragma unroll
;       for (int j = 0; j < 4; ++j) {
;         const int dist = d0 - (kt * 16 + j);
;         const bool bad = SEL ? (dist < 0) : ((unsigned)dist >= 512u);
;         const int ix = bad ? 130 : (dist > 128 ? 128 : dist);
; #pragma unroll
;         for (int hp = 0; hp < 2; ++hp) s[hp][kt][j] += tabh[hp * 132 + ix];
;       }
;   }
;   half8 pf[2];
; #pragma unroll
;   for (int hp = 0; hp < 2; ++hp) {
;     f32x4 p0, p1;
; #pragma unroll
;     for (int j = 0; j < 4; ++j) { p0[j] = __builtin_amdgcn_exp2f(s[hp][0][j]); p1[j] = __builtin_amdgcn_exp2f(s[hp][1][j]); }
;     l[hp] += ((p0[0] + p0[1]) + (p0[2] + p0[3])) + ((p1[0] + p1[1]) + (p1[2] + p1[3]));
;     pf[hp] = pack8(p0, p1);
.Lat_nogen_ya:
	v_exp_f32_e32 v198, v100
	v_exp_f32_e32 v199, v101
	v_exp_f32_e32 v200, v102
	v_exp_f32_e32 v201, v103
	v_exp_f32_e32 v202, v104
	v_exp_f32_e32 v203, v105
	v_exp_f32_e32 v204, v106
	v_exp_f32_e32 v205, v107
	v_exp_f32_e32 v206, v108
	v_exp_f32_e32 v207, v109
	v_exp_f32_e32 v208, v110
	v_exp_f32_e32 v209, v111
	v_exp_f32_e32 v210, v112
	v_exp_f32_e32 v211, v113
	v_exp_f32_e32 v212, v114
	v_exp_f32_e32 v213, v115
	v_cvt_pkrtz_f16_f32 v120, v198, v199
	v_cvt_pkrtz_f16_f32 v121, v200, v201
	v_cvt_pkrtz_f16_f32 v122, v202, v203
	v_cvt_pkrtz_f16_f32 v123, v204, v205
	v_cvt_pkrtz_f16_f32 v124, v206, v207
	v_cvt_pkrtz_f16_f32 v125, v208, v209
	v_cvt_pkrtz_f16_f32 v126, v210, v211
	v_cvt_pkrtz_f16_f32 v127, v212, v213
	s_cmp_lg_u32 s41, 0
	s_cbranch_scc1 .Lat_ytop
	s_branch .Lat_yexit
.Lat_yb:
	s_waitcnt lgkmcnt(0)
	v_subrev_u32_e32 v246, s45, v195
	s_and_b32 s44, s12, 2
	s_or_b32 s44, s44, 1
	v_mfma_f32_16x16x32_f16 v[100:103], v[96:99], v[8:11], v[128:131]
	s_add_i32 s8, s45, 128
	s_min_i32 s8, s8, s14
	s_mul_i32 s8, s8, s42
	s_mov_b32 s9, 0
	v_lshl_add_u64 v[238:239], v[240:241], 0, s[8:9]
	v_mfma_f32_16x16x32_f16 v[104:107], v[88:91], v[8:11], v[128:131]
	s_add_i32 m0, s43, s22
	s_nop 0
	global_load_lds_dwordx4 v[238:239], off
	s_add_i32 s43, s43, 0x2000
	s_cmp_eq_u32 s43, 0x1f880
	v_mfma_f32_16x16x32_f16 v[108:111], v[96:99], v[16:19], v[132:135]
	s_cselect_b32 s43, 0x20080, s43
	s_cmp_eq_u32 s43, 0x26080
	s_cselect_b32 s43, 0x19880, s43
	s_add_i32 s39, s39, 0x2000
	s_cmp_eq_u32 s39, 0x1f880
	v_mfma_f32_16x16x32_f16 v[112:115], v[88:91], v[16:19], v[132:135]
	s_cselect_b32 s39, 0x20080, s39
	s_cmp_eq_u32 s39, 0x26080
	s_cselect_b32 s39, 0x19880, s39
	s_add_i32 s45, s45, 32
	s_add_i32 s41, s41, -1
	v_mfma_f32_16x16x32_f16 v[100:103], v[92:95], v[12:15], v[100:103]
	s_add_i32 s10, s45, 0x9f
	s_cmp_gt_i32 s10, s51
	s_cselect_b32 s11, 2, 0
	s_add_i32 s10, s45, 0x1f1
	s_cmp_le_i32 s10, s51
	v_mfma_f32_16x16x32_f16 v[104:107], v[84:87], v[12:15], v[104:107]
	s_cselect_b32 s10, 2, 0
	s_and_b32 s10, s10, s4
	s_or_b32 s11, s11, s10
	s_lshr_b32 s10, s45, 6
	v_bfe_u32 v0, v244, s10, 1
	v_mfma_f32_16x16x32_f16 v[108:111], v[92:95], v[20:23], v[108:111]
	v_cmp_ne_u32_e32 vcc, 0, v0
	s_cmp_lg_u64 vcc, 0
	s_cselect_b32 s10, 1, 0
	s_lshr_b32 s9, s11, 1
	s_or_b32 s10, s10, s9
	v_mfma_f32_16x16x32_f16 v[112:115], v[84:87], v[20:23], v[112:115]
	s_cmp_le_i32 s45, s15
	s_cselect_b32 s10, s10, 0
	s_cmp_ge_i32 s45, s40
	s_cselect_b32 s10, s10, 0
	s_or_b32 s12, s11, s10
	ds_read_b128 v[80:83], v65 offset:4096
	ds_read_b128 v[76:79], v65 offset:5120
	ds_read_b128 v[72:75], v65 offset:6144
	ds_read_b128 v[68:71], v65 offset:7168
	s_bitcmp1_b32 s44, 1
	s_cbranch_scc0 .Lat_nogen_yb
	v_add_u32_e32 v116, 19, v246
	v_add_u32_e32 v117, 18, v246
	v_cmp_gt_u32_e64 s[8:9], v247, v116
	v_cmp_gt_u32_e64 vcc, v247, v117
	v_min_u32_e32 v116, 0x80, v116
	v_min_u32_e32 v117, 0x80, v117
	v_cndmask_b32_e64 v116, v161, v116, s[8:9]
	v_cndmask_b32_e64 v117, v161, v117, vcc
	v_lshl_add_u32 v116, v116, 2, s38
	v_lshl_add_u32 v117, v117, 2, s38
	ds_read2_b32 v[222:223], v116 offset1:132
	ds_read2_b32 v[224:225], v117 offset1:132
	v_add_u32_e32 v116, 17, v246
	v_add_u32_e32 v117, 16, v246
	v_cmp_gt_u32_e64 s[8:9], v247, v116
	v_cmp_gt_u32_e64 vcc, v247, v117
	v_min_u32_e32 v116, 0x80, v116
	v_min_u32_e32 v117, 0x80, v117
	v_cndmask_b32_e64 v116, v161, v116, s[8:9]
	v_cndmask_b32_e64 v117, v161, v117, vcc
	v_lshl_add_u32 v116, v116, 2, s38
	v_lshl_add_u32 v117, v117, 2, s38
	ds_read2_b32 v[226:227], v116 offset1:132
	ds_read2_b32 v[228:229], v117 offset1:132
	v_add_u32_e32 v116, 3, v246
	v_add_u32_e32 v117, 2, v246
	v_cmp_gt_u32_e64 s[8:9], v247, v116
	v_cmp_gt_u32_e64 vcc, v247, v117
	v_min_u32_e32 v116, 0x80, v116
	v_min_u32_e32 v117, 0x80, v117
	v_cndmask_b32_e64 v116, v161, v116, s[8:9]
	v_cndmask_b32_e64 v117, v161, v117, vcc
	v_lshl_add_u32 v116, v116, 2, s38
	v_lshl_add_u32 v117, v117, 2, s38
	ds_read2_b32 v[230:231], v116 offset1:132
	ds_read2_b32 v[232:233], v117 offset1:132
	v_add_u32_e32 v116, 1, v246
	v_add_u32_e32 v117, 0, v246
	v_cmp_gt_u32_e64 s[8:9], v247, v116
	v_cmp_gt_u32_e64 vcc, v247, v117
	v_min_u32_e32 v116, 0x80, v116
	v_min_u32_e32 v117, 0x80, v117
	v_cndmask_b32_e64 v116, v161, v116, s[8:9]
	v_cndmask_b32_e64 v117, v161, v117, vcc
	v_lshl_add_u32 v116, v116, 2, s38
	v_lshl_add_u32 v117, v117, 2, s38
	ds_read2_b32 v[234:235], v116 offset1:132
	ds_read2_b32 v[236:237], v117 offset1:132
	s_waitcnt lgkmcnt(0)
	v_add_f32_e32 v100, v100, v222
	v_add_f32_e32 v108, v108, v223
	v_add_f32_e32 v101, v101, v224
	v_add_f32_e32 v109, v109, v225
	v_add_f32_e32 v102, v102, v226
	v_add_f32_e32 v110, v110, v227
	v_add_f32_e32 v103, v103, v228
	v_add_f32_e32 v111, v111, v229
	v_add_f32_e32 v104, v104, v230
	v_add_f32_e32 v112, v112, v231
	v_add_f32_e32 v105, v105, v232
	v_add_f32_e32 v113, v113, v233
	v_add_f32_e32 v106, v106, v234
	v_add_f32_e32 v114, v114, v235
	v_add_f32_e32 v107, v107, v236
	v_add_f32_e32 v115, v115, v237

; #define MFMA16(a, b, c) __builtin_amdgcn_mfma_f32_16x16x32_f16((a), (b), (c), 0, 0, 0)
; #define RING_ISSUE(SI) do { int kbi = kb0 + (SI) * 32; if (kbi > kb_last) kbi = kb_last; const int slot = (SI) % 3; \
;           const h16* srcp = wave < 4 ? kbase + (size_t)kbi * LDH + k_src_off : vT + (size_t)(kbi >> 5) * 2048 + v_src_off; \
;           __builtin_amdgcn_global_load_lds((const unsigned*)srcp, (LAS unsigned*)(ring + slot * 8192 + stage_dst), 16, 0, 0); } while (0)
; template <bool SEL, bool GEN>
; DI void attn_step(const KF& kv, const int kb, const int t, const int lane, const bool selbit,
;                   const LAS float* tabh, const half8 (&q)[2][2], f32x4 (&O)[2][4], const float (&nR)[2], float (&l)[2]) {
;     ...
; #pragma unroll
;   for (int dt = 0; dt < 4; ++dt)
; #pragma unroll
;     for (int hp = 0; hp < 2; ++hp) O[hp][dt] = MFMA16(kv.v[dt], pf[hp], O[hp][dt]);
; DI void attn_phase(const Params& p, const int layer, const int wid_s) {
;     ...
;           RING_ISSUE(si + 2);
;           const int kb = kb0 + si * 32;
;           if (kb > kmax_w || kb < lo_w) continue;
;           if (br == 1 && kb + 31 + 128 <= t0 && __ballot((selmask >> (kb >> 6)) & 1u) == 0ull) continue;
.Lat_yskip:
	s_bitcmp1_b32 s44, 0
	s_cbranch_scc0 .Lat_yd
	s_waitcnt lgkmcnt(0)
	v_mfma_f32_16x16x32_f16 v[60:63], v[80:83], v[120:123], v[60:63]
	v_add_f32_e32 v214, v214, v198
	v_add_f32_e32 v215, v215, v199
	v_add_f32_e32 v216, v216, v200
	v_add_f32_e32 v217, v217, v201
	v_add_f32_e32 v214, v214, v202
	v_add_f32_e32 v215, v215, v203
	v_add_f32_e32 v216, v216, v204
	v_mfma_f32_16x16x32_f16 v[56:59], v[76:79], v[120:123], v[56:59]
	v_add_f32_e32 v217, v217, v205
	v_add_f32_e32 v218, v218, v206
	v_add_f32_e32 v219, v219, v207
	v_add_f32_e32 v220, v220, v208
	v_add_f32_e32 v221, v221, v209
	v_add_f32_e32 v218, v218, v210
	v_add_f32_e32 v219, v219, v211
	v_mfma_f32_16x16x32_f16 v[52:55], v[72:75], v[120:123], v[52:55]
	v_add_f32_e32 v220, v220, v212
	v_add_f32_e32 v221, v221, v213
	s_add_i32 s8, s45, 128
	s_min_i32 s8, s8, s14
	s_mul_i32 s8, s8, s42
	s_mov_b32 s9, 0
	v_lshl_add_u64 v[238:239], v[240:241], 0, s[8:9]
	v_mfma_f32_16x16x32_f16 v[48:51], v[68:71], v[120:123], v[48:51]
	s_add_i32 m0, s43, s22
	s_nop 0
	global_load_lds_dwordx4 v[238:239], off
	s_add_i32 s43, s43, 0x2000
	s_cmp_eq_u32 s43, 0x1f880
	s_cselect_b32 s43, 0x20080, s43
	s_cmp_eq_u32 s43, 0x26080
	v_mfma_f32_16x16x32_f16 v[44:47], v[80:83], v[124:127], v[44:47]
	s_cselect_b32 s43, 0x19880, s43
	s_add_i32 s39, s39, 0x2000
	s_cmp_eq_u32 s39, 0x1f880
	s_cselect_b32 s39, 0x20080, s39
	s_cmp_eq_u32 s39, 0x26080
	s_cselect_b32 s39, 0x19880, s39
	s_add_i32 s45, s45, 32
	v_mfma_f32_16x16x32_f16 v[40:43], v[76:79], v[124:127], v[40:43]
	s_add_i32 s41, s41, -1
	s_add_i32 s10, s45, 0x9f
	s_cmp_gt_i32 s10, s51
	s_cselect_b32 s11, 2, 0
	s_add_i32 s10, s45, 0x1f1
	s_cmp_le_i32 s10, s51
	s_cselect_b32 s10, 2, 0
	v_mfma_f32_16x16x32_f16 v[36:39], v[72:75], v[124:127], v[36:39]
	s_and_b32 s10, s10, s4
	s_or_b32 s11, s11, s10
	s_lshr_b32 s10, s45, 6
	v_bfe_u32 v0, v244, s10, 1
	v_cmp_ne_u32_e32 vcc, 0, v0
	s_cmp_lg_u64 vcc, 0
	s_cselect_b32 s10, 1, 0
	v_mfma_f32_16x16x32_f16 v[32:35], v[68:71], v[124:127], v[32:35]
	s_lshr_b32 s9, s11, 1
	s_or_b32 s10, s10, s9
	s_cmp_le_i32 s45, s15
	s_cselect_b32 s10, s10, 0
	s_cmp_ge_i32 s45, s40
	s_cselect_b32 s10, s10, 0
	s_or_b32 s12, s11, s10
	s_mov_b32 s44, 0
	s_cmp_lg_u32 s41, 0
	s_cbranch_scc1 .Lat_ytop
	s_branch .Lat_yexit

; #define MFMA16(a, b, c) __builtin_amdgcn_mfma_f32_16x16x32_f16((a), (b), (c), 0, 0, 0)
; template <bool SEL, bool GEN>
; DI void attn_step(const KF& kv, const int kb, const int t, const int lane, const bool selbit,
;                   const LAS float* tabh, const half8 (&q)[2][2], f32x4 (&O)[2][4], const float (&nR)[2], float (&l)[2]) {
;     ...
; #pragma unroll
;   for (int dt = 0; dt < 4; ++dt)
; #pragma unroll
;     for (int hp = 0; hp < 2; ++hp) O[hp][dt] = MFMA16(kv.v[dt], pf[hp], O[hp][dt]);
.Lat_yexit:
	s_bitcmp1_b32 s44, 0
	s_cbranch_scc0 .Lat_done
	s_waitcnt lgkmcnt(0)
	v_mfma_f32_16x16x32_f16 v[60:63], v[80:83], v[120:123], v[60:63]
	v_add_f32_e32 v214, v214, v198
	v_add_f32_e32 v215, v215, v199
	v_mfma_f32_16x16x32_f16 v[56:59], v[76:79], v[120:123], v[56:59]
	v_add_f32_e32 v216, v216, v200
	v_add_f32_e32 v217, v217, v201
	v_mfma_f32_16x16x32_f16 v[52:55], v[72:75], v[120:123], v[52:55]
	v_add_f32_e32 v214, v214, v202
	v_add_f32_e32 v215, v215, v203
	v_mfma_f32_16x16x32_f16 v[48:51], v[68:71], v[120:123], v[48:51]
	v_add_f32_e32 v216, v216, v204
	v_add_f32_e32 v217, v217, v205
	v_mfma_f32_16x16x32_f16 v[44:47], v[80:83], v[124:127], v[44:47]
	v_add_f32_e32 v218, v218, v206
	v_add_f32_e32 v219, v219, v207
	v_mfma_f32_16x16x32_f16 v[40:43], v[76:79], v[124:127], v[40:43]
	v_add_f32_e32 v220, v220, v208
	v_add_f32_e32 v221, v221, v209
	v_mfma_f32_16x16x32_f16 v[36:39], v[72:75], v[124:127], v[36:39]
	v_add_f32_e32 v218, v218, v210
	v_add_f32_e32 v219, v219, v211
	v_mfma_f32_16x16x32_f16 v[32:35], v[68:71], v[124:127], v[32:35]
	v_add_f32_e32 v220, v220, v212
	v_add_f32_e32 v221, v221, v213
